# plus P2 queues: one shared counter for the three unit lists (one unsuccessful pop per workgroup instead of three)
# speedup vs baseline: 1.0160x; 1.0009x over previous
.Lq_have_p:
	v_add_u32_e32 v1, 0xffffff80, v1
	v_cmp_lt_i32_e32 vcc, s87, v1
	v_readfirstlane_b32 s2, v1
	s_cbranch_vccnz .Lq_exit_p
	s_ashr_i32 s0, s2, 2
	s_and_b32 s4, s2, 3
	s_sub_i32 s5, 63, s0
	s_lshl_b32 s2, s4, 11
	s_lshl_b32 s89, s5, 5
	s_add_i32 s13, s89, s2
	v_or_b32_e32 v74, s13, v152
	v_lshlrev_b64 v[2:3], 10, v[74:75]
	v_or_b32_e32 v74, s13, v150
	v_readlane_b32 s0, v252, 17
	v_lshlrev_b64 v[18:19], 5, v[74:75]
	v_readlane_b32 s1, v252, 18
	v_lshl_add_u64 v[14:15], v[76:77], 0, v[2:3]
	global_load_dwordx4 v[2:5], v[14:15], off offset:48
	global_load_dwordx4 v[6:9], v[14:15], off offset:32
	global_load_dwordx4 v[10:13], v[14:15], off offset:16
	s_nop 0
	global_load_dwordx4 v[14:17], v[14:15], off
	v_lshl_add_u64 v[18:19], s[0:1], 0, v[18:19]
	global_load_dwordx4 v[20:23], v[18:19], off
	global_load_dwordx4 v[24:27], v[18:19], off offset:16
	s_cmp_le_i32 s88, s5
	s_cselect_b64 s[0:1], -1, 0
	s_cmp_gt_i32 s88, s5
	s_waitcnt vmcnt(2)
	ds_write_b128 v160, v[14:17]
	ds_write_b128 v160, v[10:13] offset:16
	ds_write_b128 v160, v[6:9] offset:32
	ds_write_b128 v160, v[2:5] offset:48
	s_waitcnt vmcnt(1)
	v_mul_f32_e32 v18, 0x3d3504f3, v20
	s_waitcnt vmcnt(0)
	v_mul_f32_e32 v20, 0x3d3504f3, v24
	v_mul_f32_e32 v1, 0x3d3504f3, v21
	v_mul_f32_e32 v19, 0x3d3504f3, v25
	v_mul_f32_e32 v22, 0x3d3504f3, v22
	v_mul_f32_e32 v24, 0x3d3504f3, v26
	v_mul_f32_e32 v21, 0x3d3504f3, v23
	v_mul_f32_e32 v23, 0x3d3504f3, v27
	s_waitcnt lgkmcnt(0)
	s_barrier
	s_cbranch_scc1 .LBB0_709
	v_add_u32_e32 v2, s2, v153
	v_mov_b32_e32 v3, v75
	v_lshlrev_b64 v[2:3], 7, v[2:3]
	v_lshl_add_u64 v[2:3], v[78:79], 0, v[2:3]
	global_load_dwordx4 v[26:29], v[2:3], off
	global_load_dwordx4 v[30:33], v[2:3], off offset:32
	global_load_dwordx4 v[34:37], v[2:3], off offset:64
	global_load_dwordx4 v[38:41], v[2:3], off offset:96
	s_branch .LBB0_710
